# combine_merge rows: 6 slab loads issued together (was 4 serialized round trips per row)
# speedup vs baseline: 1.0025x; 1.0025x over previous
; #define GAS __attribute__((address_space(1)))
; __device__ __forceinline__ unsigned cvt_pk_bf16(float lo, float hi) { const f32x2 v = {lo, hi}; return __builtin_bit_cast(unsigned, __builtin_convertvector(v, bf16n2)); }
; __device__ __forceinline__ float bf_lo(unsigned u) { return __uint_as_float(u << 16); }
; __device__ __forceinline__ float bf_hi(unsigned u) { return __uint_as_float(u & 0xffff0000u); }
; __device__ __forceinline__ void combine_merge(Frame& F) {
;     ...
;     for (int x = gw; x < nrows; x += NGW) { const int j = x >> 8, r = x & 255; int pm, pn; S.tile_of(S.G + j, pm, pn);
;         const GAS bf16* p = sl + (size_t)(MERGE_TAIL * j) * 65536 + (size_t)r * 256 + 4 * lane;
;         f32x4 v = {0.f, 0.f, 0.f, 0.f};
; #pragma unroll
;         for (int q = 0; q < MERGE_TAIL; ++q) { const v2u t = *(const GAS v2u*)(p + (size_t)q * 65536); v += (f32x4){bf_lo(t.x), bf_hi(t.x), bf_lo(t.y), bf_hi(t.y)}; }
;         v2u o; o.x = cvt_pk_bf16(v[0], v[1]); o.y = cvt_pk_bf16(v[2], v[3]); *(GAS v2u*)(M + (size_t)(256 * pm + r) * 1024 + 256 * pn + 4 * lane) = o; }
.LBB0_1121:
	s_ashr_i32 s9, s17, 3
	s_add_i32 s9, s24, s9
	s_ashr_i32 s17, s9, 31
	s_lshr_b32 s17, s17, 30
	s_add_i32 s17, s9, s17
	s_ashr_i32 s24, s17, 2
	s_sub_i32 s25, 0x49, s24
	s_min_i32 s25, s25, 1
	s_abs_i32 s27, s25
	v_cvt_f32_u32_e32 v2, s27
	s_sub_i32 s36, 0, s27
	s_and_b32 s17, s17, -4
	s_sub_i32 s17, s9, s17
	v_rcp_iflag_f32_e32 v2, v2
	s_abs_i32 s26, s17
	s_xor_b32 s9, s17, s25
	s_and_b32 s8, s16, 0xff
	v_mul_f32_e32 v2, 0x4f7ffffe, v2
	v_cvt_u32_f32_e32 v2, v2
	s_ashr_i32 s9, s9, 31
	v_readfirstlane_b32 s37, v2
	s_mul_i32 s36, s36, s37
	s_mul_hi_u32 s36, s37, s36
	s_add_i32 s37, s37, s36
	s_mul_hi_u32 s36, s26, s37
	s_mul_i32 s37, s36, s27
	s_sub_i32 s26, s26, s37
	s_add_i32 s37, s36, 1
	s_sub_i32 s52, s26, s27
	s_cmp_ge_u32 s26, s27
	s_cselect_b32 s36, s37, s36
	s_cselect_b32 s26, s52, s26
	s_add_i32 s37, s36, 1
	s_cmp_ge_u32 s26, s27
	s_cselect_b32 s26, s37, s36
	s_xor_b32 s26, s26, s9
	s_sub_i32 s9, s26, s9
	s_mul_i32 s25, s9, s25
	s_sub_i32 s17, s17, s25
	s_add_i32 s17, s24, s17
	s_mul_i32 s24, s20, 6
	s_ashr_i32 s25, s24, 31
	s_lshl_b64 s[24:25], s[24:25], 17
	s_add_u32 s20, s12, s24
	s_addc_u32 s25, s13, s25
	s_lshl_b32 s24, s8, 9
	s_add_u32 s24, s20, s24
	s_addc_u32 s25, s25, 0
	global_load_dwordx2 v[4:5], v0, s[24:25]
	s_add_u32 s24, s24, 0x20000
	s_addc_u32 s25, s25, 0
	global_load_dwordx2 v[8:9], v0, s[24:25]
	s_add_u32 s24, s24, 0x20000
	s_addc_u32 s25, s25, 0
	global_load_dwordx2 v[10:11], v0, s[24:25]
	s_add_u32 s24, s24, 0x20000
	s_addc_u32 s25, s25, 0
	global_load_dwordx2 v[12:13], v0, s[24:25]
	s_add_u32 s24, s24, 0x20000
	s_addc_u32 s25, s25, 0
	global_load_dwordx2 v[14:15], v0, s[24:25]
	s_add_u32 s24, s24, 0x20000
	s_addc_u32 s25, s25, 0
	global_load_dwordx2 v[2:3], v0, s[24:25]
	s_lshl_b32 s17, s17, 8
	s_or_b32 s24, s17, s8
	s_ashr_i32 s25, s24, 31
	s_lshl_b64 s[24:25], s[24:25], 11
	s_add_u32 s17, s14, s24
	s_addc_u32 s20, s15, s25
	s_lshl_b32 s8, s9, 8
	s_ashr_i32 s9, s8, 31
	s_lshl_b64 s[8:9], s[8:9], 1
	s_add_u32 s8, s17, s8
	s_addc_u32 s9, s20, s9
	s_add_i32 s16, s16, s66
	s_waitcnt vmcnt(5)
	v_lshlrev_b32_e32 v6, 16, v4
	v_and_b32_e32 v7, 0xffff0000, v4
	v_lshlrev_b32_e32 v16, 16, v5
	v_and_b32_e32 v17, 0xffff0000, v5
	v_pk_add_f32 v[16:17], v[16:17], 0 op_sel_hi:[1,0]
	v_pk_add_f32 v[6:7], v[6:7], 0 op_sel_hi:[1,0]
	s_waitcnt vmcnt(4)
	v_lshlrev_b32_e32 v18, 16, v9
	v_and_b32_e32 v19, 0xffff0000, v9
	v_pk_add_f32 v[16:17], v[16:17], v[18:19]
	v_lshlrev_b32_e32 v18, 16, v8
	v_and_b32_e32 v19, 0xffff0000, v8
	v_pk_add_f32 v[6:7], v[6:7], v[18:19]
	s_waitcnt vmcnt(3)
	v_lshlrev_b32_e32 v18, 16, v11
	v_and_b32_e32 v19, 0xffff0000, v11
	v_pk_add_f32 v[16:17], v[16:17], v[18:19]
	v_lshlrev_b32_e32 v18, 16, v10
	v_and_b32_e32 v19, 0xffff0000, v10
	v_pk_add_f32 v[6:7], v[6:7], v[18:19]
	s_waitcnt vmcnt(2)
	v_lshlrev_b32_e32 v18, 16, v13
	v_and_b32_e32 v19, 0xffff0000, v13
	v_pk_add_f32 v[16:17], v[16:17], v[18:19]
	v_lshlrev_b32_e32 v18, 16, v12
	v_and_b32_e32 v19, 0xffff0000, v12
	v_pk_add_f32 v[6:7], v[6:7], v[18:19]
	s_waitcnt vmcnt(1)
	v_lshlrev_b32_e32 v18, 16, v15
	v_and_b32_e32 v19, 0xffff0000, v15
	v_pk_add_f32 v[16:17], v[16:17], v[18:19]
	v_lshlrev_b32_e32 v18, 16, v14
	v_and_b32_e32 v19, 0xffff0000, v14
	v_pk_add_f32 v[6:7], v[6:7], v[18:19]
	s_waitcnt vmcnt(0)
	v_lshlrev_b32_e32 v18, 16, v3
	v_and_b32_e32 v19, 0xffff0000, v3
	v_pk_add_f32 v[16:17], v[16:17], v[18:19]
	v_lshlrev_b32_e32 v18, 16, v2
	v_and_b32_e32 v19, 0xffff0000, v2
	v_pk_add_f32 v[6:7], v[6:7], v[18:19]
	v_cvt_pk_bf16_f32 v4, v6, v7
	v_cvt_pk_bf16_f32 v5, v16, v17
	v_lshl_add_u64 v[2:3], s[8:9], 0, v[0:1]
	v_readlane_b32 s8, v242, 37
	s_cmp_lt_i32 s16, s8
	global_store_dwordx2 v[2:3], v[4:5], off
	s_cbranch_scc0 .LBB0_1126
